# context-row norm publish: write-through (sc1) stores of the 2 context rows per workgroup replace the per-workgroup L2 writeback fence
# speedup vs baseline: 1.0273x; 1.0048x over previous
; __device__ __forceinline__ unsigned pk2(float lo, float hi) { const f32x2cv v = {lo, hi}; return __builtin_bit_cast(unsigned, __builtin_convertvector(v, bf16x2cv)); }
; template <int NS> __device__ __forceinline__ void ctx_norm_rows(Frame& F, const Args& AR, bool first, const float* comb, int c0) {
;     ...
;         { const float tot = (red[half * 4 + 0] + red[half * 4 + 1]) + (red[half * 4 + 2] + red[half * 4 + 3]); const float rs = rsqrtf(tot * (1.0f / DM) + 1e-6f);
; #pragma unroll
;           for (int j = 0; j < 2; ++j) x[j] += vg[j] * (y[j] * rs); }
;         ss = 0.f;
; #pragma unroll
;         for (int j = 0; j < 2; ++j) ss += (x[j].x * x[j].x + x[j].y * x[j].y) + (x[j].z * x[j].z + x[j].w * x[j].w);
;         ss = wave_sum(ss);
;         if (F.lane == 0) red[8 + half * 4 + seg] = ss;
;         __syncthreads();
;         { const float tot = (red[8 + half * 4 + 0] + red[8 + half * 4 + 1]) + (red[8 + half * 4 + 2] + red[8 + half * 4 + 3]); const float rs = rsqrtf(tot * (1.0f / DM) + 1e-6f);
; #pragma unroll
;           for (int j = 0; j < 2; ++j) { v2u o; o.x = pk2(x[j].x, x[j].y); o.y = pk2(x[j].z, x[j].w); *(v2u*)(Xb + (size_t)r * DM + co + 256 * j) = o;
;               const f32x4 hv = x[j] * rs * vs[j] + vh[j]; v2u h; h.x = pk2(hv.x, hv.y); h.y = pk2(hv.z, hv.w); *(v2u*)(H + (size_t)r * DM + co + 256 * j) = h; } }
;     ...
;     asm volatile("s_waitcnt vmcnt(0)" ::: "memory");
;     __syncthreads();
;     if (threadIdx.x == 0) { __builtin_amdgcn_fence(__ATOMIC_RELEASE, "agent"); asm volatile("s_waitcnt vmcnt(0)" ::: "memory");
;         __hip_atomic_fetch_add((unsigned*)(F.ws + WS_CTL) + CW_CTXRDY + 64 * idx, 1u, __ATOMIC_RELAXED, __HIP_MEMORY_SCOPE_AGENT); }
.LBB0_530:
	s_or_b64 exec, exec, s[0:1]
	v_mov_b32_e32 v22, s8
	s_waitcnt lgkmcnt(0)
	s_barrier
	ds_read_b128 v[22:25], v22 offset:32
	s_mov_b32 s0, 0x800000
	s_waitcnt lgkmcnt(0)
	v_mov_b32_e32 v32, v23
	v_mov_b32_e32 v33, v24
	v_mov_b32_e32 v23, v25
	v_pk_add_f32 v[22:23], v[32:33], v[22:23]
	v_cvt_pk_bf16_f32 v32, v30, v31
	v_add_f32_e32 v22, v22, v23
	v_fmamk_f32 v22, v22, 0x3a000000, v199
	v_mul_f32_e32 v23, 0x4b800000, v22
	v_cmp_gt_f32_e32 vcc, s0, v22
	v_cvt_pk_bf16_f32 v33, v28, v29
	global_store_dwordx2 v[26:27], v[32:33], off sc1
	v_cndmask_b32_e32 v22, v22, v23, vcc
	v_rsq_f32_e32 v24, v22
	v_lshl_add_u64 v[22:23], s[94:95], 0, v[194:195]
	v_lshl_add_u64 v[22:23], v[22:23], 0, s[4:5]
	v_mul_f32_e32 v25, 0x45800000, v24
	v_cndmask_b32_e32 v24, v24, v25, vcc
	v_pk_mul_f32 v[30:31], v[30:31], v[24:25] op_sel_hi:[1,0]
	v_pk_mul_f32 v[28:29], v[28:29], v[24:25] op_sel_hi:[1,0]
	s_waitcnt vmcnt(2)
	v_pk_fma_f32 v[10:11], v[10:11], v[30:31], v[14:15]
	v_pk_fma_f32 v[12:13], v[12:13], v[28:29], v[16:17]
	v_cvt_pk_bf16_f32 v10, v10, v11
	v_cvt_pk_bf16_f32 v11, v12, v13
	global_store_dwordx2 v[22:23], v[10:11], off sc1
	v_cvt_pk_bf16_f32 v10, v20, v21
	v_cvt_pk_bf16_f32 v11, v18, v19
	global_store_dwordx2 v[26:27], v[10:11], off offset:512 sc1
	v_pk_mul_f32 v[10:11], v[20:21], v[24:25] op_sel_hi:[1,0]
	v_pk_mul_f32 v[12:13], v[18:19], v[24:25] op_sel_hi:[1,0]
	s_waitcnt vmcnt(3)
	v_pk_fma_f32 v[2:3], v[2:3], v[10:11], v[6:7]
	v_pk_fma_f32 v[4:5], v[4:5], v[12:13], v[8:9]
	v_cvt_pk_bf16_f32 v2, v2, v3
	v_cvt_pk_bf16_f32 v3, v4, v5
	global_store_dwordx2 v[22:23], v[2:3], off offset:512 sc1
.LBB0_531:
	s_waitcnt vmcnt(0)
	s_barrier
	s_and_saveexec_b64 s[0:1], s[92:93]
	s_cbranch_execz .LBB0_534
	s_mov_b64 s[4:5], exec
	v_mbcnt_lo_u32_b32 v2, s4, 0
	s_waitcnt vmcnt(0)
	s_waitcnt vmcnt(0)
	v_mbcnt_hi_u32_b32 v2, s5, v2
	v_cmp_eq_u32_e32 vcc, 0, v2
	s_and_b64 s[8:9], exec, vcc
	s_mov_b64 exec, s[8:9]
	s_cbranch_execz .LBB0_534
	v_readlane_b32 s8, v250, 58
	v_readlane_b32 s9, v250, 59
	s_mov_b32 s7, s9
	s_lshl_b32 s8, s6, 6
	v_writelane_b32 v250, s6, 58
	s_nop 1
	v_writelane_b32 v250, s7, 59
	s_lshl_b64 s[6:7], s[8:9], 2
	v_readlane_b32 s8, v251, 4
	s_add_u32 s6, s8, s6
	v_readlane_b32 s8, v251, 5
	s_addc_u32 s7, s8, s7
	s_bcnt1_i32_b64 s4, s[4:5]
	v_mov_b32_e32 v2, s4
	global_atomic_add v195, v2, s[6:7]

; __device__ __forceinline__ unsigned pk2(float lo, float hi) { const f32x2cv v = {lo, hi}; return __builtin_bit_cast(unsigned, __builtin_convertvector(v, bf16x2cv)); }
; template <int NS> __device__ __forceinline__ void ctx_norm_rows(Frame& F, const Args& AR, bool first, const float* comb, int c0) {
;     ...
;         { const float tot = (red[half * 4 + 0] + red[half * 4 + 1]) + (red[half * 4 + 2] + red[half * 4 + 3]); const float rs = rsqrtf(tot * (1.0f / DM) + 1e-6f);
; #pragma unroll
;           for (int j = 0; j < 2; ++j) x[j] += vg[j] * (y[j] * rs); }
;         ss = 0.f;
; #pragma unroll
;         for (int j = 0; j < 2; ++j) ss += (x[j].x * x[j].x + x[j].y * x[j].y) + (x[j].z * x[j].z + x[j].w * x[j].w);
;         ss = wave_sum(ss);
;         if (F.lane == 0) red[8 + half * 4 + seg] = ss;
;         __syncthreads();
;         { const float tot = (red[8 + half * 4 + 0] + red[8 + half * 4 + 1]) + (red[8 + half * 4 + 2] + red[8 + half * 4 + 3]); const float rs = rsqrtf(tot * (1.0f / DM) + 1e-6f);
; #pragma unroll
;           for (int j = 0; j < 2; ++j) { v2u o; o.x = pk2(x[j].x, x[j].y); o.y = pk2(x[j].z, x[j].w); *(v2u*)(Xb + (size_t)r * DM + co + 256 * j) = o;
;               const f32x4 hv = x[j] * rs * vs[j] + vh[j]; v2u h; h.x = pk2(hv.x, hv.y); h.y = pk2(hv.z, hv.w); *(v2u*)(H + (size_t)r * DM + co + 256 * j) = h; } }
;     }
.LBB0_1033:
	s_or_b64 exec, exec, s[8:9]
	v_mov_b32_e32 v26, s13
	s_waitcnt lgkmcnt(0)
	s_barrier
	ds_read_b128 v[26:29], v26 offset:32
	v_cvt_pk_bf16_f32 v32, v22, v23
	v_cvt_pk_bf16_f32 v33, v24, v25
	s_addk_i32 s16, 0x8a
	s_waitcnt lgkmcnt(0)
	v_mov_b32_e32 v30, v27
	v_mov_b32_e32 v31, v28
	v_mov_b32_e32 v27, v29
	v_pk_add_f32 v[26:27], v[30:31], v[26:27]
	s_nop 0
	v_add_f32_e32 v26, v26, v27
	v_fmamk_f32 v26, v26, 0x3a000000, v199
	v_mul_f32_e32 v27, 0x4b800000, v26
	v_cmp_gt_f32_e32 vcc, s7, v26
	s_ashr_i32 s7, s6, 31
	s_lshl_b64 s[8:9], s[6:7], 12
	v_cndmask_b32_e32 v26, v26, v27, vcc
	v_rsq_f32_e32 v26, v26
	v_lshl_add_u64 v[30:31], v[138:139], 0, s[8:9]
	v_lshl_add_u64 v[28:29], v[134:135], 0, s[8:9]
	s_addk_i32 s6, 0x114
	v_mul_f32_e32 v27, 0x45800000, v26
	v_cndmask_b32_e32 v26, v26, v27, vcc
	v_pk_mul_f32 v[22:23], v[22:23], v[26:27] op_sel_hi:[1,0]
	v_pk_mul_f32 v[24:25], v[24:25], v[26:27] op_sel_hi:[1,0]
	v_pk_fma_f32 v[10:11], v[10:11], v[22:23], v[14:15]
	v_pk_fma_f32 v[12:13], v[12:13], v[24:25], v[16:17]
	v_cvt_pk_bf16_f32 v10, v10, v11
	v_cvt_pk_bf16_f32 v11, v12, v13
	global_store_dwordx2 v[30:31], v[10:11], off sc1
	v_cvt_pk_bf16_f32 v10, v18, v19
	v_cvt_pk_bf16_f32 v11, v20, v21
	global_store_dwordx2 v[28:29], v[10:11], off offset:512 sc1
	v_pk_mul_f32 v[10:11], v[18:19], v[26:27] op_sel_hi:[1,0]
	v_pk_mul_f32 v[12:13], v[20:21], v[26:27] op_sel_hi:[1,0]
	v_pk_fma_f32 v[2:3], v[2:3], v[10:11], v[6:7]
	v_pk_fma_f32 v[4:5], v[4:5], v[12:13], v[8:9]
	v_cvt_pk_bf16_f32 v2, v2, v3
	v_cvt_pk_bf16_f32 v3, v4, v5
	s_cmp_lt_u32 s16, 0x80000100
	global_store_dwordx2 v[28:29], v[32:33], off sc1
	global_store_dwordx2 v[30:31], v[2:3], off offset:512 sc1
	s_cbranch_scc0 .LBB0_1042

;     ...
;     asm volatile("s_waitcnt vmcnt(0)" ::: "memory");
;     __syncthreads();
;     if (threadIdx.x == 0) { __builtin_amdgcn_fence(__ATOMIC_RELEASE, "agent"); asm volatile("s_waitcnt vmcnt(0)" ::: "memory");
;         __hip_atomic_fetch_add((unsigned*)(F.ws + WS_CTL) + CW_CTXRDY + 64 * idx, 1u, __ATOMIC_RELAXED, __HIP_MEMORY_SCOPE_AGENT); }
.LBB0_1042:
	s_waitcnt vmcnt(0)
	s_waitcnt vmcnt(0)
	s_barrier
	s_and_saveexec_b64 s[0:1], s[92:93]
	s_cbranch_execz .LBB0_1045
	s_mov_b64 s[4:5], exec
	v_mbcnt_lo_u32_b32 v2, s4, 0
	s_waitcnt vmcnt(0)
	v_mbcnt_hi_u32_b32 v2, s5, v2
	v_cmp_eq_u32_e32 vcc, 0, v2
	s_and_b64 s[6:7], exec, vcc
	s_mov_b64 exec, s[6:7]
	s_cbranch_execz .LBB0_1045
	v_readlane_b32 s8, v250, 58
	v_readlane_b32 s9, v250, 59
	v_readlane_b32 s6, v254, 15
	s_mov_b32 s7, s9
	s_mul_i32 s8, s6, 0xc0
	v_writelane_b32 v250, s6, 58
	s_nop 1
	v_writelane_b32 v250, s7, 59
	s_lshl_b64 s[6:7], s[8:9], 2
	v_readlane_b32 s8, v251, 4
	s_add_u32 s6, s8, s6
	v_readlane_b32 s8, v251, 5
	s_addc_u32 s7, s8, s7
	s_bcnt1_i32_b64 s4, s[4:5]
	v_mov_b32_e32 v2, s4
	global_atomic_add v195, v2, s[6:7]

; __device__ __forceinline__ unsigned pk2(float lo, float hi) { const f32x2cv v = {lo, hi}; return __builtin_bit_cast(unsigned, __builtin_convertvector(v, bf16x2cv)); }
; template <int NS> __device__ __forceinline__ void ctx_norm_rows(Frame& F, const Args& AR, bool first, const float* comb, int c0) {
;     ...
;         { const float tot = (red[half * 4 + 0] + red[half * 4 + 1]) + (red[half * 4 + 2] + red[half * 4 + 3]); const float rs = rsqrtf(tot * (1.0f / DM) + 1e-6f);
; #pragma unroll
;           for (int j = 0; j < 2; ++j) x[j] += vg[j] * (y[j] * rs); }
;         ss = 0.f;
; #pragma unroll
;         for (int j = 0; j < 2; ++j) ss += (x[j].x * x[j].x + x[j].y * x[j].y) + (x[j].z * x[j].z + x[j].w * x[j].w);
;         ss = wave_sum(ss);
;         if (F.lane == 0) red[8 + half * 4 + seg] = ss;
;         __syncthreads();
;         { const float tot = (red[8 + half * 4 + 0] + red[8 + half * 4 + 1]) + (red[8 + half * 4 + 2] + red[8 + half * 4 + 3]); const float rs = rsqrtf(tot * (1.0f / DM) + 1e-6f);
; #pragma unroll
;           for (int j = 0; j < 2; ++j) { v2u o; o.x = pk2(x[j].x, x[j].y); o.y = pk2(x[j].z, x[j].w); *(v2u*)(Xb + (size_t)r * DM + co + 256 * j) = o;
;               const f32x4 hv = x[j] * rs * vs[j] + vh[j]; v2u h; h.x = pk2(hv.x, hv.y); h.y = pk2(hv.z, hv.w); *(v2u*)(H + (size_t)r * DM + co + 256 * j) = h; } }
;     ...
;     asm volatile("s_waitcnt vmcnt(0)" ::: "memory");
;     __syncthreads();
;     if (threadIdx.x == 0) { __builtin_amdgcn_fence(__ATOMIC_RELEASE, "agent"); asm volatile("s_waitcnt vmcnt(0)" ::: "memory");
;         __hip_atomic_fetch_add((unsigned*)(F.ws + WS_CTL) + CW_CTXRDY + 64 * idx, 1u, __ATOMIC_RELAXED, __HIP_MEMORY_SCOPE_AGENT); }
.LBB0_1948:
	s_or_b64 exec, exec, s[0:1]
	v_mov_b32_e32 v22, s10
	s_waitcnt lgkmcnt(0)
	s_barrier
	ds_read_b128 v[22:25], v22 offset:32
	s_mov_b32 s0, 0x800000
	v_lshl_add_u64 v[30:31], s[6:7], 0, v[194:195]
	s_waitcnt lgkmcnt(0)
	v_mov_b32_e32 v32, v23
	v_mov_b32_e32 v33, v24
	v_mov_b32_e32 v23, v25
	v_pk_add_f32 v[22:23], v[32:33], v[22:23]
	v_cvt_pk_bf16_f32 v24, v28, v29
	v_add_f32_e32 v22, v22, v23
	v_fmamk_f32 v22, v22, 0x3a000000, v199
	v_cmp_gt_f32_e32 vcc, s0, v22
	v_mul_f32_e32 v23, 0x4b800000, v22
	v_cvt_pk_bf16_f32 v25, v26, v27
	v_cndmask_b32_e32 v22, v22, v23, vcc
	v_rsq_f32_e32 v22, v22
	global_store_dwordx2 v[30:31], v[24:25], off sc1
	s_add_u32 s0, s94, s4
	s_addc_u32 s1, s95, s5
	v_mul_f32_e32 v23, 0x45800000, v22
	v_cndmask_b32_e32 v22, v22, v23, vcc
	v_pk_mul_f32 v[24:25], v[28:29], v[22:23] op_sel_hi:[1,0]
	v_pk_mul_f32 v[26:27], v[26:27], v[22:23] op_sel_hi:[1,0]
	v_pk_fma_f32 v[10:11], v[10:11], v[24:25], v[14:15]
	v_pk_fma_f32 v[12:13], v[12:13], v[26:27], v[16:17]
	v_cvt_pk_bf16_f32 v10, v10, v11
	v_cvt_pk_bf16_f32 v11, v12, v13
	global_store_dwordx2 v194, v[10:11], s[0:1] sc1
	v_cvt_pk_bf16_f32 v10, v20, v21
	v_cvt_pk_bf16_f32 v11, v18, v19
	global_store_dwordx2 v[30:31], v[10:11], off offset:512 sc1
	v_pk_mul_f32 v[10:11], v[20:21], v[22:23] op_sel_hi:[1,0]
	v_pk_mul_f32 v[12:13], v[18:19], v[22:23] op_sel_hi:[1,0]
	v_pk_fma_f32 v[2:3], v[2:3], v[10:11], v[6:7]
	v_pk_fma_f32 v[4:5], v[4:5], v[12:13], v[8:9]
	v_cvt_pk_bf16_f32 v2, v2, v3
	v_cvt_pk_bf16_f32 v3, v4, v5
	global_store_dwordx2 v194, v[2:3], s[0:1] offset:512 sc1
.LBB0_1949:
	s_waitcnt vmcnt(0)
	s_waitcnt vmcnt(0)
	s_barrier
	s_and_saveexec_b64 s[0:1], s[92:93]
	s_cbranch_execz .LBB0_1952
	s_mov_b64 s[4:5], exec
	v_mbcnt_lo_u32_b32 v2, s4, 0
	s_waitcnt vmcnt(0)
	v_mbcnt_hi_u32_b32 v2, s5, v2
	v_cmp_eq_u32_e32 vcc, 0, v2
	s_and_b64 s[6:7], exec, vcc
	s_mov_b64 exec, s[6:7]
	s_cbranch_execz .LBB0_1952
	v_readlane_b32 s6, v250, 58
	v_readlane_b32 s7, v250, 59
	s_mov_b32 s11, s7
	s_lshl_b32 s10, s8, 6
	v_writelane_b32 v250, s6, 58
	v_readlane_b32 s9, v251, 4
	s_nop 0
	v_writelane_b32 v250, s7, 59
	s_lshl_b64 s[6:7], s[10:11], 2
	s_add_u32 s6, s9, s6
	v_readlane_b32 s9, v251, 5
	s_addc_u32 s7, s9, s7
	s_bcnt1_i32_b64 s4, s[4:5]
	v_mov_b32_e32 v2, s4
	global_atomic_add v195, v2, s[6:7]
